# v16 + barrier after conversion phase split: weights released after w_in_a transposes (64-bit group count with XCC fields), x conversion behind it, group barrier + top-counter check at the end; fallbac
# speedup vs baseline: 1.0046x; 1.0028x over previous
; __device__ __forceinline__ unsigned xb_ld(unsigned* p)              { return __hip_atomic_load(p, __ATOMIC_RELAXED, __HIP_MEMORY_SCOPE_AGENT); }
; __device__ __forceinline__ unsigned xb_add(unsigned* p, unsigned v) { return __hip_atomic_fetch_add(p, v, __ATOMIC_RELAXED, __HIP_MEMORY_SCOPE_AGENT); }
; #define XB_SPIN(cond, bar) do { unsigned _sp = 0; while (cond) { __builtin_amdgcn_s_sleep(1); \
;     if ((++_sp & 255u) == 0u) { if (xb_ld(&(bar)[XB_TMO])) break; if (_sp > XB_SPIN_CAP) { atomicAdd(&(bar)[XB_TMO], 1u); break; } } } } while (0)
; __device__ __forceinline__ void xcd_barrier(const XcdBarrier& b) {
;     asm volatile("s_waitcnt vmcnt(0)" ::: "memory");
;     __syncthreads();
;     if (threadIdx.x == 0) {
;         unsigned* bar = b.bar;
;         __builtin_amdgcn_s_waitcnt(0);
;         unsigned nloc = b.st[0], nx = b.st[1];
;         if (nloc == 0u) { xcd_barrier_complete(bar, b.x, nloc, nx); b.st[0] = nloc; b.st[1] = nx; }
;         const unsigned old = xb_add(&bar[XB_XSUB(b.x)], 1u);
;         const unsigned gen = old / nloc;
;         if (old + 1u == (gen + 1u) * nloc) {
;             __builtin_amdgcn_fence(__ATOMIC_RELEASE, "agent");
;             asm volatile("s_waitcnt vmcnt(0)" ::: "memory");
;             const unsigned og = xb_add(&bar[XB_TOP], 1u);
;             const unsigned tg = og / nx;
;             if (og + 1u == (tg + 1u) * nx) xb_add(&bar[XB_TOPGEN], 1u);
;             else XB_SPIN(xb_ld(&bar[XB_TOPGEN]) == tg, bar);
;             __builtin_amdgcn_fence(__ATOMIC_ACQUIRE, "agent");
;             xb_add(&bar[XB_XGEN(b.x)], 1u);
;             asm volatile("s_waitcnt vmcnt(0)" ::: "memory");
;         } else {
;             XB_SPIN(xb_ld(&bar[XB_XGEN(b.x)]) == gen, bar);
;             __builtin_amdgcn_fence(__ATOMIC_ACQUIRE, "agent");
;             asm volatile("s_waitcnt vmcnt(0)" ::: "memory");
;         }
;     }
;     __syncthreads();
; }
; __global__ void __launch_bounds__(NTHREADS, 2) mk_fwd(Params P) {
;     ...
;         if (G == 256) convert_rows_xcd(P.x, SLOTA, G, bid); else convert_flat(P.x, SLOTA, (size_t)MTOK * DM, G, bid);
.LBB0_76:
	s_and_b64 vcc, exec, s[18:19]
	s_cbranch_vccz .LBB0_93
	s_waitcnt vmcnt(0)
	s_barrier
	s_and_saveexec_b64 s[100:101], s[12:13]
	s_cbranch_execz .Ls0_na
	s_and_b32 s98, s2, 7
	s_lshl_b32 s98, s98, 6
	s_add_i32 s98, s98, 0x8000
	v_mov_b32_e32 v251, s98
	s_mul_i32 s3, s33, 6
	s_lshl_b64 s[98:99], 1, s3
	s_or_b32 s99, s99, 0x10000
	v_mov_b32_e32 v252, s98
	v_mov_b32_e32 v253, s99
	global_atomic_add_x2 v[254:255], v251, v[252:253], s[54:55] offset:32 sc0
	s_waitcnt vmcnt(0)
	v_readfirstlane_b32 s98, v254
	v_readfirstlane_b32 s99, v255
	s_lshr_b32 s3, s99, 16
	s_cmp_eq_u32 s3, 31
	s_cbranch_scc0 .Ls0_na
	s_mul_i32 s3, s33, 6
	s_lshr_b64 s[98:99], s[98:99], s3
	s_and_b32 s98, s98, 63
	v_mov_b32_e32 v252, 1
	v_mov_b32_e32 v251, 0x8280
	s_cmp_eq_u32 s98, 31
	s_cbranch_scc0 .Ls0_fb
	buffer_wbl2 sc1
	s_waitcnt vmcnt(0)
	v_mov_b32_e32 v251, 0x8240
.Ls0_fb:
	global_atomic_add v251, v252, s[54:55]
.Ls0_na:
	s_or_b64 exec, exec, s[100:101]
	s_ashr_i32 s0, s2, 3
	s_ashr_i32 s1, s0, 31
	s_lshl_b64 s[0:1], s[0:1], 9
	v_lshl_add_u64 v[32:33], s[0:1], 0, v[164:165]
	s_mov_b64 s[4:5], 0x40000
	v_cmp_gt_u64_e32 vcc, s[4:5], v[32:33]
	s_and_saveexec_b64 s[10:11], vcc
	s_cbranch_execz .LBB0_92
	s_lshl_b32 s3, s2, 18
	s_and_b32 s3, s3, 0x1c0000
	s_add_u32 s0, s3, s0
	s_addc_u32 s1, 0, s1
	s_waitcnt vmcnt(5)
	v_lshl_add_u64 v[0:1], s[0:1], 0, v[164:165]
	v_lshl_add_u64 v[2:3], v[0:1], 4, s[40:41]
	s_mov_b64 s[0:1], 0x40c0000
	v_lshlrev_b64 v[0:1], 5, v[0:1]
	v_lshl_add_u64 v[34:35], v[2:3], 0, s[0:1]
	v_lshl_add_u64 v[0:1], s[16:17], 0, v[0:1]
	s_mov_b64 s[0:1], 0x180010
	v_lshl_add_u64 v[36:37], v[0:1], 0, s[0:1]
	v_mov_b32_e32 v0, 0
	s_mov_b32 s18, 0xffe7fff0
	s_mov_b32 s26, 0xffeffff0
	s_mov_b32 s60, 0xfff7fff0
	s_mov_b64 s[16:17], 0
	s_mov_b32 s19, -1
	s_mov_b32 s3, 0xffe80000
	s_mov_b64 s[20:21], 0x3c000
	s_mov_b32 s27, -1
	s_mov_b64 s[36:37], 0x38000
	s_mov_b32 s61, -1
	s_mov_b64 s[62:63], 0x34000
	s_mov_b64 s[64:65], 0x10000
	s_mov_b64 s[66:67], 0x100000
	s_mov_b64 s[68:69], 0x200000
	s_mov_b64 s[70:71], 0x2ffff
	v_mov_b32_e32 v1, v0
	v_mov_b32_e32 v2, v0
	v_mov_b32_e32 v3, v0
	s_waitcnt vmcnt(4)
	v_mov_b32_e32 v4, v0
	v_mov_b32_e32 v5, v0
	v_mov_b32_e32 v6, v0
	v_mov_b32_e32 v7, v0
	s_waitcnt vmcnt(3)
	v_mov_b32_e32 v8, v0
	v_mov_b32_e32 v9, v0
	v_mov_b32_e32 v10, v0
	v_mov_b32_e32 v11, v0
	v_mov_b32_e32 v16, v0
	v_mov_b32_e32 v17, v0
	v_mov_b32_e32 v18, v0
	v_mov_b32_e32 v19, v0
	v_mov_b32_e32 v20, v0
	v_mov_b32_e32 v21, v0
	v_mov_b32_e32 v22, v0
	v_mov_b32_e32 v23, v0
	s_waitcnt vmcnt(2)
	v_mov_b32_e32 v12, v0
	v_mov_b32_e32 v13, v0
	v_mov_b32_e32 v14, v0
	v_mov_b32_e32 v15, v0
	s_branch .LBB0_80

; __device__ __forceinline__ unsigned xb_ld(unsigned* p)              { return __hip_atomic_load(p, __ATOMIC_RELAXED, __HIP_MEMORY_SCOPE_AGENT); }
; __device__ __forceinline__ unsigned xb_add(unsigned* p, unsigned v) { return __hip_atomic_fetch_add(p, v, __ATOMIC_RELAXED, __HIP_MEMORY_SCOPE_AGENT); }
; #define XB_SPIN(cond, bar) do { unsigned _sp = 0; while (cond) { __builtin_amdgcn_s_sleep(1); \
;     if ((++_sp & 255u) == 0u) { if (xb_ld(&(bar)[XB_TMO])) break; if (_sp > XB_SPIN_CAP) { atomicAdd(&(bar)[XB_TMO], 1u); break; } } } } while (0)
; #define SEAM(k) do { if (IN(k) && hi > (k) + 1) xcd_barrier(xbar); } while (0)
; __device__ __forceinline__ void xcd_barrier(const XcdBarrier& b) {
;     asm volatile("s_waitcnt vmcnt(0)" ::: "memory");
;     __syncthreads();
;     if (threadIdx.x == 0) {
;         unsigned* bar = b.bar;
;         __builtin_amdgcn_s_waitcnt(0);
;         unsigned nloc = b.st[0], nx = b.st[1];
;         if (nloc == 0u) { xcd_barrier_complete(bar, b.x, nloc, nx); b.st[0] = nloc; b.st[1] = nx; }
;         const unsigned old = xb_add(&bar[XB_XSUB(b.x)], 1u);
;         const unsigned gen = old / nloc;
;         if (old + 1u == (gen + 1u) * nloc) {
;             __builtin_amdgcn_fence(__ATOMIC_RELEASE, "agent");
;             asm volatile("s_waitcnt vmcnt(0)" ::: "memory");
;             const unsigned og = xb_add(&bar[XB_TOP], 1u);
;             const unsigned tg = og / nx;
;             if (og + 1u == (tg + 1u) * nx) xb_add(&bar[XB_TOPGEN], 1u);
;             else XB_SPIN(xb_ld(&bar[XB_TOPGEN]) == tg, bar);
;             __builtin_amdgcn_fence(__ATOMIC_ACQUIRE, "agent");
;             xb_add(&bar[XB_XGEN(b.x)], 1u);
;             asm volatile("s_waitcnt vmcnt(0)" ::: "memory");
;         } else {
;             XB_SPIN(xb_ld(&bar[XB_XGEN(b.x)]) == gen, bar);
;             __builtin_amdgcn_fence(__ATOMIC_ACQUIRE, "agent");
;             asm volatile("s_waitcnt vmcnt(0)" ::: "memory");
;         }
;     }
;     __syncthreads();
; }
; __global__ void __launch_bounds__(NTHREADS, 2) mk_fwd(Params P) {
;     ...
;     SEAM(0);
.LBB0_93:
	s_cmp_gt_i32 s43, 1
	s_cselect_b64 s[0:1], -1, 0
	s_and_b64 s[4:5], s[8:9], s[0:1]
	s_andn2_b64 vcc, exec, s[4:5]
	s_cbranch_vccnz .LBB0_143
	s_waitcnt vmcnt(0)
	s_waitcnt lgkmcnt(0)
	s_barrier
	s_and_saveexec_b64 s[4:5], s[12:13]
	s_cbranch_execz .LBB0_142
	s_and_b32 s98, s2, 7
	s_lshl_b32 s98, s98, 6
	s_add_i32 s98, s98, 0x8000
	v_mov_b32_e32 v250, s98
	v_mov_b32_e32 v252, 1
	v_mov_b32_e32 v253, 0x8240
	v_mov_b32_e32 v254, 0x8280
	s_waitcnt vmcnt(0)
	global_atomic_add v250, v252, s[54:55] offset:24
	s_mov_b32 s99, 0
.Ls0_spin:
	global_load_dword v251, v250, s[54:55] offset:24 sc1
	global_load_dword v255, v253, s[54:55] sc1
	global_load_dword v249, v254, s[54:55] sc1
	s_waitcnt vmcnt(0)
	v_readfirstlane_b32 s98, v249
	s_cmp_lg_u32 s98, 0
	s_cbranch_scc1 .Ls0_orig
	v_readfirstlane_b32 s98, v251
	s_cmp_ge_u32 s98, 32
	s_cbranch_scc0 .Ls0_retry
	v_readfirstlane_b32 s98, v255
	s_cmp_ge_u32 s98, 8
	s_cbranch_scc1 .Ls0_ok

; __device__ __forceinline__ unsigned xb_add(unsigned* p, unsigned v) { return __hip_atomic_fetch_add(p, v, __ATOMIC_RELAXED, __HIP_MEMORY_SCOPE_AGENT); }
; __device__ __forceinline__ void xcd_barrier(const XcdBarrier& b) {
;     asm volatile("s_waitcnt vmcnt(0)" ::: "memory");
;     __syncthreads();
;     if (threadIdx.x == 0) {
;         unsigned* bar = b.bar;
;         __builtin_amdgcn_s_waitcnt(0);
;         unsigned nloc = b.st[0], nx = b.st[1];
;         if (nloc == 0u) { xcd_barrier_complete(bar, b.x, nloc, nx); b.st[0] = nloc; b.st[1] = nx; }
;         const unsigned old = xb_add(&bar[XB_XSUB(b.x)], 1u);
;         const unsigned gen = old / nloc;
;         if (old + 1u == (gen + 1u) * nloc) {
.Ls0_ok:
	buffer_inv sc1
	s_waitcnt vmcnt(0)
	s_branch .LBB0_142
.Ls0_orig:
	s_add_i32 s3, 0, 0x20000
	s_waitcnt vmcnt(5)
	v_mov_b32_e32 v0, s3
	s_waitcnt vmcnt(0) expcnt(0) lgkmcnt(0)
	ds_read_b32 v2, v0
	s_add_i32 s3, 0, 0x20004
	v_mov_b32_e32 v0, s3
	ds_read_b32 v0, v0
	s_waitcnt lgkmcnt(1)
	v_cmp_ne_u32_e32 vcc, 0, v2
	s_cbranch_vccnz .LBB0_110
	s_add_u32 s6, s40, 0x3d00200
	s_addc_u32 s7, s41, 0
	s_add_u32 s8, s40, 0x3d00400
	s_addc_u32 s9, s41, 0
	s_add_u32 s10, s40, 0x3d00500
	s_addc_u32 s11, s41, 0
	s_add_u32 s16, s40, 0x3d00600
	s_addc_u32 s17, s41, 0
	s_add_u32 s18, s40, 0x3d00700
	s_addc_u32 s19, s41, 0
	s_add_u32 s20, s40, 0x3d00800
	s_addc_u32 s21, s41, 0
	s_add_u32 s26, s40, 0x3d00900
	s_addc_u32 s27, s41, 0
	s_add_u32 s36, s40, 0x3d00a00
	s_addc_u32 s37, s41, 0
	s_add_u32 s60, s40, 0x3d00b00
	s_addc_u32 s61, s41, 0
	s_add_u32 s62, s40, 0x3d00c00
	s_addc_u32 s63, s41, 0
	s_add_u32 s64, s40, 0x3d00d00
	s_addc_u32 s65, s41, 0
	s_add_u32 s66, s40, 0x3d00e00
	s_addc_u32 s67, s41, 0
	s_add_u32 s68, s40, 0x3d00f00
	s_addc_u32 s69, s41, 0
	s_add_u32 s70, s40, 0x3d01000
	s_addc_u32 s71, s41, 0
	s_add_u32 s72, s40, 0x3d01100
	s_addc_u32 s73, s41, 0
	s_add_u32 s74, s40, 0x3d01200
	s_addc_u32 s75, s41, 0
	s_mul_i32 s3, s35, s92
	s_add_u32 s76, s40, 0x3d01300
	s_mul_i32 s3, s3, s34
	s_addc_u32 s77, s41, 0
	s_mov_b32 s84, 1
	v_mov_b32_e32 v16, 0
	s_branch .LBB0_98
